# diff-attention S-role: K-fragment LDS read addresses 16->9 VALU per step, loop-head s_nop removed (precompute gives MFMA->VALU distance), on top of K-DMA offset precompute
# baseline (speedup 1.0000x reference)
.LBB0_1360:
	v_max_f32_e32 v101, v5, v5
	v_max_f32_e32 v103, v4, v4
	v_max_f32_e32 v101, v103, v101
	v_max3_f32 v101, v101, v6, v7
	v_max3_f32 v101, v101, v8, v9
	v_max3_f32 v101, v101, v10, v11
	v_max3_f32 v101, v101, v12, v13
	v_max3_f32 v101, v101, v14, v15
	v_max3_f32 v101, v101, v16, v17
	v_max3_f32 v101, v101, v18, v19
	v_max3_f32 v101, v101, v20, v21
	v_max3_f32 v101, v101, v22, v23
	v_max3_f32 v101, v101, v24, v25
	v_max3_f32 v101, v101, v26, v27
	v_max3_f32 v101, v101, v28, v29
	v_max3_f32 v101, v101, v30, v31
	v_max3_f32 v101, v101, v32, v33
	v_max3_f32 v101, v101, v34, v35
	v_mov_b32_e32 v103, v101
	s_nop 1
	v_permlane32_swap_b32_e32 v101, v103
	v_max_f32_e32 v103, v103, v103
	v_max_f32_e32 v101, v101, v101
	v_max_f32_e32 v101, v101, v103
	v_sub_f32_e32 v103, v101, v102
	v_cmp_ge_f32_e32 vcc, s34, v103
	v_max_f32_e32 v103, v102, v102
	v_max_f32_e32 v103, v103, v101
	v_sub_f32_e32 v101, v102, v103
	v_mul_f32_e32 v101, 0x3fb8aa3b, v101
	v_exp_f32_e32 v101, v101
	s_cmp_eq_u64 vcc, exec
	s_cselect_b64 vcc, -1, 0
	v_cndmask_b32_e64 v101, v101, 1.0, vcc
	v_cmp_gt_f32_e64 s[0:1], 1.0, v101
	s_cmp_lg_u64 s[0:1], 0
	s_cselect_b64 s[0:1], -1, 0
	s_and_b64 s[78:79], s[0:1], s[2:3]
	s_and_saveexec_b64 s[20:21], s[78:79]
	ds_write_b32 v2, v101
	s_or_b64 exec, exec, s[20:21]
	s_and_saveexec_b64 s[20:21], s[4:5]
	v_cndmask_b32_e64 v104, 0, 1, s[0:1]
	s_add_i32 s0, s59, 0
	s_add_i32 s0, s0, 0x20000
	v_mov_b32_e32 v105, s0
	ds_write_b32 v105, v104
	s_or_b64 exec, exec, s[20:21]
	s_add_i32 s0, s70, -3
	s_cmp_ge_u32 s0, s36
	v_add_u32_e32 v104, s72, v184
	s_cbranch_scc1 .LBB0_1366
	s_mul_hi_u32 s0, s68, 0xaaaaaaab
	s_lshr_b32 s0, s0, 1
	s_mul_i32 s0, s0, 0xc000
	s_sub_i32 s98, s72, s0
	v_add_u32_e32 v251, s98, v184
	v_add_u32_e32 v47, v251, v190
	v_add_u32_e32 v40, v251, v192
	v_add_u32_e32 v41, v251, v194
	v_add_u32_e32 v42, v251, v196
	v_add_u32_e32 v43, v251, v198
	v_add_u32_e32 v44, v251, v200
	v_add_u32_e32 v45, v251, v202
	v_add_u32_e32 v46, v251, v203
	ds_read_b128 v[36:39], v47
	ds_read_b128 v[106:109], v40
	ds_read_b128 v[114:117], v41
	ds_read_b128 v[122:125], v42
	ds_read_b128 v[130:133], v43
	ds_read_b128 v[138:141], v44
	ds_read_b128 v[146:149], v45
	ds_read_b128 v[214:217], v46
	ds_read_b128 v[52:55], v47 offset:8192
	ds_read_b128 v[110:113], v40 offset:8192
	ds_read_b128 v[118:121], v41 offset:8192
	ds_read_b128 v[126:129], v42 offset:8192
	ds_read_b128 v[134:137], v43 offset:8192
	ds_read_b128 v[142:145], v44 offset:8192
	ds_read_b128 v[150:153], v45 offset:8192
	ds_read_b128 v[218:221], v46 offset:8192
	s_waitcnt lgkmcnt(14)
	v_mfma_f32_32x32x16_bf16 v[36:51], v[36:39], v[68:71], 0
	v_cndmask_b32_e32 v102, v103, v102, vcc
	v_mul_f32_e32 v103, 0xbfb8aa3b, v102
	v_fmamk_f32 v4, v4, 0x3fb8aa3b, v103
	v_fmamk_f32 v5, v5, 0x3fb8aa3b, v103
	v_exp_f32_e32 v4, v4
	v_fmamk_f32 v6, v6, 0x3fb8aa3b, v103
	v_exp_f32_e32 v5, v5
	v_mfma_f32_32x32x16_bf16 v[36:51], v[106:109], v[72:75], v[36:51]
	v_fmamk_f32 v7, v7, 0x3fb8aa3b, v103
	v_exp_f32_e32 v6, v6
	v_fmamk_f32 v8, v8, 0x3fb8aa3b, v103
	v_fmamk_f32 v9, v9, 0x3fb8aa3b, v103
	v_fmamk_f32 v10, v10, 0x3fb8aa3b, v103
	v_fmamk_f32 v11, v11, 0x3fb8aa3b, v103
	v_fmamk_f32 v12, v12, 0x3fb8aa3b, v103
	s_waitcnt lgkmcnt(13)
	v_mfma_f32_32x32x16_bf16 v[36:51], v[114:117], v[76:79], v[36:51]
	v_fmamk_f32 v13, v13, 0x3fb8aa3b, v103
	v_fmamk_f32 v14, v14, 0x3fb8aa3b, v103
	v_fmamk_f32 v15, v15, 0x3fb8aa3b, v103
	v_fmamk_f32 v16, v16, 0x3fb8aa3b, v103
	v_fmamk_f32 v17, v17, 0x3fb8aa3b, v103
	v_fmamk_f32 v18, v18, 0x3fb8aa3b, v103
	v_fmamk_f32 v19, v19, 0x3fb8aa3b, v103
	v_fmamk_f32 v20, v20, 0x3fb8aa3b, v103
	s_waitcnt lgkmcnt(12)
	v_mfma_f32_32x32x16_bf16 v[36:51], v[122:125], v[80:83], v[36:51]
	v_fmamk_f32 v21, v21, 0x3fb8aa3b, v103
	v_fmamk_f32 v22, v22, 0x3fb8aa3b, v103
	v_fmamk_f32 v23, v23, 0x3fb8aa3b, v103
	v_fmamk_f32 v24, v24, 0x3fb8aa3b, v103
	v_fmamk_f32 v25, v25, 0x3fb8aa3b, v103
	v_fmamk_f32 v26, v26, 0x3fb8aa3b, v103
	v_fmamk_f32 v27, v27, 0x3fb8aa3b, v103
	v_fmamk_f32 v28, v28, 0x3fb8aa3b, v103
	s_waitcnt lgkmcnt(11)
	v_mfma_f32_32x32x16_bf16 v[36:51], v[130:133], v[84:87], v[36:51]
	v_fmamk_f32 v29, v29, 0x3fb8aa3b, v103
	v_fmamk_f32 v30, v30, 0x3fb8aa3b, v103
	v_fmamk_f32 v31, v31, 0x3fb8aa3b, v103
	v_fmamk_f32 v32, v32, 0x3fb8aa3b, v103
	v_fmamk_f32 v33, v33, 0x3fb8aa3b, v103
	v_fmamk_f32 v34, v34, 0x3fb8aa3b, v103
	v_fmac_f32_e32 v103, 0x3fb8aa3b, v35
	v_exp_f32_e32 v7, v7
	s_waitcnt lgkmcnt(10)
	v_mfma_f32_32x32x16_bf16 v[36:51], v[138:141], v[88:91], v[36:51]
	v_exp_f32_e32 v8, v8
	v_exp_f32_e32 v35, v103
	v_add_f32_e32 v103, 0, v4
	v_exp_f32_e32 v9, v9
	s_waitcnt lgkmcnt(9)
	v_mfma_f32_32x32x16_bf16 v[36:51], v[146:149], v[92:95], v[36:51]
	v_add_f32_e32 v103, v5, v103
	v_exp_f32_e32 v10, v10
	v_add_f32_e32 v103, v6, v103
	v_exp_f32_e32 v11, v11
	v_add_f32_e32 v103, v7, v103
	v_exp_f32_e32 v12, v12
	s_waitcnt lgkmcnt(8)
	v_mfma_f32_32x32x16_bf16 v[36:51], v[214:217], v[96:99], v[36:51]
	v_add_f32_e32 v103, v8, v103
	v_exp_f32_e32 v13, v13
	v_add_f32_e32 v103, v9, v103
	v_exp_f32_e32 v14, v14
	v_add_f32_e32 v103, v10, v103
	s_waitcnt lgkmcnt(7)
	v_mfma_f32_32x32x16_bf16 v[52:67], v[52:55], v[68:71], 0
	v_exp_f32_e32 v15, v15
	v_add_f32_e32 v103, v11, v103
	v_exp_f32_e32 v16, v16
	v_add_f32_e32 v103, v12, v103
	v_exp_f32_e32 v17, v17
	s_waitcnt lgkmcnt(6)
	v_mfma_f32_32x32x16_bf16 v[52:67], v[110:113], v[72:75], v[52:67]
	v_add_f32_e32 v103, v13, v103
	v_exp_f32_e32 v18, v18
	v_add_f32_e32 v103, v14, v103
	v_exp_f32_e32 v19, v19
	v_add_f32_e32 v103, v15, v103
	v_exp_f32_e32 v20, v20
	s_waitcnt lgkmcnt(5)
	v_mfma_f32_32x32x16_bf16 v[52:67], v[118:121], v[76:79], v[52:67]
	v_add_f32_e32 v103, v16, v103
	v_exp_f32_e32 v21, v21
	v_add_f32_e32 v103, v17, v103
	v_exp_f32_e32 v22, v22
	v_add_f32_e32 v103, v18, v103
	s_waitcnt lgkmcnt(4)
	v_mfma_f32_32x32x16_bf16 v[52:67], v[126:129], v[80:83], v[52:67]
	v_exp_f32_e32 v23, v23
	v_add_f32_e32 v103, v19, v103
	v_exp_f32_e32 v24, v24
	v_add_f32_e32 v103, v20, v103
	v_exp_f32_e32 v25, v25
	s_waitcnt lgkmcnt(3)
	v_mfma_f32_32x32x16_bf16 v[52:67], v[134:137], v[84:87], v[52:67]
	v_add_f32_e32 v103, v21, v103
	v_exp_f32_e32 v26, v26
	v_add_f32_e32 v103, v22, v103
	v_exp_f32_e32 v27, v27
	v_add_f32_e32 v103, v23, v103
	v_exp_f32_e32 v28, v28
	s_waitcnt lgkmcnt(2)
	v_mfma_f32_32x32x16_bf16 v[52:67], v[142:145], v[88:91], v[52:67]
	v_add_f32_e32 v103, v24, v103
	v_exp_f32_e32 v29, v29
	v_add_f32_e32 v103, v25, v103
	v_exp_f32_e32 v30, v30
	v_add_f32_e32 v103, v26, v103
	s_waitcnt lgkmcnt(1)
	v_mfma_f32_32x32x16_bf16 v[52:67], v[150:153], v[92:95], v[52:67]
	v_exp_f32_e32 v31, v31
	v_add_f32_e32 v103, v27, v103
	v_exp_f32_e32 v32, v32
	v_add_f32_e32 v103, v28, v103
	v_exp_f32_e32 v33, v33
	s_waitcnt lgkmcnt(0)
	v_mfma_f32_32x32x16_bf16 v[52:67], v[218:221], v[96:99], v[52:67]
	v_add_f32_e32 v103, v29, v103
	v_exp_f32_e32 v34, v34
	v_add_f32_e32 v103, v30, v103
	v_add_f32_e32 v103, v31, v103
	v_add_f32_e32 v103, v32, v103
	v_add_f32_e32 v103, v33, v103
	v_add_f32_e32 v103, v34, v103
	s_branch .Lds_join_s0

.LBB0_1373:
	s_mul_hi_u32 s0, s69, 0xaaaaaaab
	s_lshr_b32 s0, s0, 1
	s_mul_i32 s0, s0, 0xc000
	s_sub_i32 s98, s72, s0
	v_add_u32_e32 v251, s98, v184
	v_add_u32_e32 v15, v251, v201
	v_add_u32_e32 v14, v251, v199
	v_add_u32_e32 v13, v251, v197
	v_add_u32_e32 v12, v251, v195
	v_add_u32_e32 v11, v251, v193
	v_add_u32_e32 v10, v251, v191
	v_add_u32_e32 v9, v251, v189
	v_add_u32_e32 v8, v251, v186
	ds_read_b128 v[4:7], v15
	ds_read_b128 v[110:113], v14
	ds_read_b128 v[118:121], v13
	ds_read_b128 v[126:129], v12
	ds_read_b128 v[134:137], v11
	ds_read_b128 v[142:145], v10
	ds_read_b128 v[150:153], v9
	ds_read_b128 v[218:221], v8
	ds_read_b128 v[20:23], v15 offset:8192
	ds_read_b128 v[114:117], v14 offset:8192
	ds_read_b128 v[122:125], v13 offset:8192
	ds_read_b128 v[130:133], v12 offset:8192
	ds_read_b128 v[138:141], v11 offset:8192
	ds_read_b128 v[146:149], v10 offset:8192
	ds_read_b128 v[214:217], v9 offset:8192
	ds_read_b128 v[222:225], v8 offset:8192
	s_waitcnt lgkmcnt(14)
	v_mfma_f32_32x32x16_bf16 v[4:19], v[4:7], v[68:71], 0
	v_cndmask_b32_e32 v102, v108, v102, vcc
	v_mul_f32_e32 v104, 0xbfb8aa3b, v102
	v_fmamk_f32 v36, v36, 0x3fb8aa3b, v104
	v_fmamk_f32 v37, v37, 0x3fb8aa3b, v104
	v_exp_f32_e32 v36, v36
	v_fmamk_f32 v38, v38, 0x3fb8aa3b, v104
	v_exp_f32_e32 v37, v37
	v_mfma_f32_32x32x16_bf16 v[4:19], v[110:113], v[72:75], v[4:19]
	v_fmamk_f32 v39, v39, 0x3fb8aa3b, v104
	v_exp_f32_e32 v38, v38
	v_fmamk_f32 v40, v40, 0x3fb8aa3b, v104
	v_exp_f32_e32 v39, v39
	v_add_f32_e32 v105, v105, v106
	v_fmamk_f32 v41, v41, 0x3fb8aa3b, v104
	s_waitcnt lgkmcnt(13)
	v_mfma_f32_32x32x16_bf16 v[4:19], v[118:121], v[76:79], v[4:19]
	v_exp_f32_e32 v40, v40
	v_fmac_f32_e32 v105, v100, v101
	v_add_f32_e32 v100, 0, v36
	v_fmamk_f32 v42, v42, 0x3fb8aa3b, v104
	v_exp_f32_e32 v41, v41
	v_add_f32_e32 v100, v37, v100
	v_fmamk_f32 v43, v43, 0x3fb8aa3b, v104
	s_waitcnt lgkmcnt(12)
	v_mfma_f32_32x32x16_bf16 v[4:19], v[126:129], v[80:83], v[4:19]
	v_exp_f32_e32 v42, v42
	v_add_f32_e32 v100, v38, v100
	v_fmamk_f32 v44, v44, 0x3fb8aa3b, v104
	v_exp_f32_e32 v43, v43
	v_add_f32_e32 v100, v39, v100
	v_fmamk_f32 v45, v45, 0x3fb8aa3b, v104
	s_waitcnt lgkmcnt(11)
	v_mfma_f32_32x32x16_bf16 v[4:19], v[134:137], v[84:87], v[4:19]
	v_exp_f32_e32 v44, v44
	v_add_f32_e32 v100, v40, v100
	v_fmamk_f32 v46, v46, 0x3fb8aa3b, v104
	v_exp_f32_e32 v45, v45
	v_add_f32_e32 v100, v41, v100
	v_fmamk_f32 v47, v47, 0x3fb8aa3b, v104
	v_exp_f32_e32 v46, v46
	s_waitcnt lgkmcnt(10)
	v_mfma_f32_32x32x16_bf16 v[4:19], v[142:145], v[88:91], v[4:19]
	v_add_f32_e32 v100, v42, v100
	v_fmamk_f32 v48, v48, 0x3fb8aa3b, v104
	v_exp_f32_e32 v47, v47
	v_add_f32_e32 v100, v43, v100
	v_fmamk_f32 v49, v49, 0x3fb8aa3b, v104
	v_exp_f32_e32 v48, v48
	s_waitcnt lgkmcnt(9)
	v_mfma_f32_32x32x16_bf16 v[4:19], v[150:153], v[92:95], v[4:19]
	v_add_f32_e32 v100, v44, v100
	v_fmamk_f32 v50, v50, 0x3fb8aa3b, v104
	v_exp_f32_e32 v49, v49
	v_add_f32_e32 v100, v45, v100
	v_fmamk_f32 v51, v51, 0x3fb8aa3b, v104
	v_exp_f32_e32 v50, v50
	s_waitcnt lgkmcnt(8)
	v_mfma_f32_32x32x16_bf16 v[4:19], v[218:221], v[96:99], v[4:19]
	v_add_f32_e32 v100, v46, v100
	v_fmamk_f32 v52, v52, 0x3fb8aa3b, v104
	v_exp_f32_e32 v51, v51
	v_add_f32_e32 v100, v47, v100
	v_fmamk_f32 v53, v53, 0x3fb8aa3b, v104
	v_exp_f32_e32 v52, v52
	s_waitcnt lgkmcnt(7)
	v_mfma_f32_32x32x16_bf16 v[20:35], v[20:23], v[68:71], 0
	v_add_f32_e32 v100, v48, v100
	v_fmamk_f32 v54, v54, 0x3fb8aa3b, v104
	v_exp_f32_e32 v53, v53
	v_add_f32_e32 v100, v49, v100
	v_fmamk_f32 v55, v55, 0x3fb8aa3b, v104
	v_exp_f32_e32 v54, v54
	s_waitcnt lgkmcnt(6)
	v_mfma_f32_32x32x16_bf16 v[20:35], v[114:117], v[72:75], v[20:35]
	v_add_f32_e32 v100, v50, v100
	v_fmamk_f32 v56, v56, 0x3fb8aa3b, v104
	v_exp_f32_e32 v55, v55
	v_add_f32_e32 v100, v51, v100
	v_fmamk_f32 v57, v57, 0x3fb8aa3b, v104
	v_exp_f32_e32 v56, v56
	v_add_f32_e32 v100, v52, v100
	s_waitcnt lgkmcnt(5)
	v_mfma_f32_32x32x16_bf16 v[20:35], v[122:125], v[76:79], v[20:35]
	v_fmamk_f32 v58, v58, 0x3fb8aa3b, v104
	v_exp_f32_e32 v57, v57
	v_add_f32_e32 v100, v53, v100
	v_fmamk_f32 v59, v59, 0x3fb8aa3b, v104
	v_exp_f32_e32 v58, v58
	v_add_f32_e32 v100, v54, v100
	s_waitcnt lgkmcnt(4)
	v_mfma_f32_32x32x16_bf16 v[20:35], v[130:133], v[80:83], v[20:35]
	v_fmamk_f32 v60, v60, 0x3fb8aa3b, v104
	v_exp_f32_e32 v59, v59
	v_add_f32_e32 v100, v55, v100
	v_fmamk_f32 v61, v61, 0x3fb8aa3b, v104
	v_exp_f32_e32 v60, v60
	v_add_f32_e32 v100, v56, v100
	v_fmamk_f32 v62, v62, 0x3fb8aa3b, v104
	s_waitcnt lgkmcnt(3)
	v_mfma_f32_32x32x16_bf16 v[20:35], v[138:141], v[84:87], v[20:35]
	v_exp_f32_e32 v61, v61
	v_add_f32_e32 v100, v57, v100
	v_fmamk_f32 v63, v63, 0x3fb8aa3b, v104
	v_exp_f32_e32 v62, v62
	v_add_f32_e32 v100, v58, v100
	v_fmamk_f32 v64, v64, 0x3fb8aa3b, v104
	s_waitcnt lgkmcnt(2)
	v_mfma_f32_32x32x16_bf16 v[20:35], v[146:149], v[88:91], v[20:35]
	v_exp_f32_e32 v63, v63
	v_add_f32_e32 v100, v59, v100
	v_fmamk_f32 v65, v65, 0x3fb8aa3b, v104
	v_exp_f32_e32 v64, v64
	v_add_f32_e32 v100, v60, v100
	v_fmamk_f32 v66, v66, 0x3fb8aa3b, v104
	v_exp_f32_e32 v65, v65
	s_waitcnt lgkmcnt(1)
	v_mfma_f32_32x32x16_bf16 v[20:35], v[214:217], v[92:95], v[20:35]
	v_add_f32_e32 v100, v61, v100
	v_fmac_f32_e32 v104, 0x3fb8aa3b, v67
	v_exp_f32_e32 v66, v66
	v_add_f32_e32 v100, v62, v100
	v_exp_f32_e32 v67, v104
	s_waitcnt lgkmcnt(0)
	v_mfma_f32_32x32x16_bf16 v[20:35], v[222:225], v[96:99], v[20:35]
	v_add_f32_e32 v100, v63, v100
	v_add_f32_e32 v100, v64, v100
	v_add_f32_e32 v100, v65, v100
	v_add_f32_e32 v100, v66, v100
	v_add_f32_e32 v100, v67, v100
	v_mov_b32_e32 v101, v100
	s_nop 1
	v_permlane32_swap_b32_e32 v100, v101
	s_branch .Lds_join_s1

.LBB0_1392:
	v_max_f32_e32 v101, v5, v5
	v_max_f32_e32 v103, v4, v4
	v_max_f32_e32 v101, v103, v101
	v_max3_f32 v101, v101, v6, v7
	v_max3_f32 v101, v101, v8, v9
	v_max3_f32 v101, v101, v10, v11
	v_max3_f32 v101, v101, v12, v13
	v_max3_f32 v101, v101, v14, v15
	v_max3_f32 v101, v101, v16, v17
	v_max3_f32 v101, v101, v18, v19
	v_max3_f32 v101, v101, v20, v21
	v_max3_f32 v101, v101, v22, v23
	v_max3_f32 v101, v101, v24, v25
	v_max3_f32 v101, v101, v26, v27
	v_max3_f32 v101, v101, v28, v29
	v_max3_f32 v101, v101, v30, v31
	v_max3_f32 v101, v101, v32, v33
	v_max3_f32 v101, v101, v34, v35
	v_mov_b32_e32 v103, v101
	s_nop 1
	v_permlane32_swap_b32_e32 v101, v103
	v_max_f32_e32 v103, v103, v103
	v_max_f32_e32 v101, v101, v101
	v_max_f32_e32 v101, v101, v103
	v_sub_f32_e32 v103, v101, v102
	v_cmp_ge_f32_e32 vcc, s34, v103
	v_max_f32_e32 v103, v102, v102
	v_max_f32_e32 v103, v103, v101
	v_sub_f32_e32 v101, v102, v103
	v_mul_f32_e32 v101, 0x3fb8aa3b, v101
	v_exp_f32_e32 v101, v101
	s_cmp_eq_u64 vcc, exec
	s_cselect_b64 vcc, -1, 0
	v_cndmask_b32_e64 v101, v101, 1.0, vcc
	v_cmp_gt_f32_e64 s[0:1], 1.0, v101
	s_cmp_lg_u64 s[0:1], 0
	s_cselect_b64 s[0:1], -1, 0
	s_and_b64 s[66:67], s[0:1], s[2:3]
	s_and_saveexec_b64 s[14:15], s[66:67]
	ds_write_b32 v2, v101
	s_or_b64 exec, exec, s[14:15]
	s_and_saveexec_b64 s[14:15], s[4:5]
	v_cndmask_b32_e64 v104, 0, 1, s[0:1]
	s_add_i32 s0, s19, 0
	s_add_i32 s0, s0, 0x20000
	v_mov_b32_e32 v105, s0
	ds_write_b32 v105, v104
	s_or_b64 exec, exec, s[14:15]
	s_add_i32 s0, s58, -3
	s_cmp_ge_u32 s0, s36
	v_add_u32_e32 v104, s60, v184
	s_cbranch_scc1 .LBB0_1398
	s_mul_hi_u32 s0, s56, 0xaaaaaaab
	s_lshr_b32 s0, s0, 1
	s_mul_i32 s0, s0, 0xc000
	s_sub_i32 s98, s60, s0
	v_add_u32_e32 v251, s98, v184
	v_add_u32_e32 v47, v251, v190
	v_add_u32_e32 v40, v251, v192
	v_add_u32_e32 v41, v251, v194
	v_add_u32_e32 v42, v251, v196
	v_add_u32_e32 v43, v251, v198
	v_add_u32_e32 v44, v251, v200
	v_add_u32_e32 v45, v251, v202
	v_add_u32_e32 v46, v251, v203
	ds_read_b128 v[36:39], v47
	ds_read_b128 v[106:109], v40
	ds_read_b128 v[114:117], v41
	ds_read_b128 v[122:125], v42
	ds_read_b128 v[130:133], v43
	ds_read_b128 v[138:141], v44
	ds_read_b128 v[146:149], v45
	ds_read_b128 v[154:157], v46
	ds_read_b128 v[52:55], v47 offset:8192
	ds_read_b128 v[110:113], v40 offset:8192
	ds_read_b128 v[118:121], v41 offset:8192
	ds_read_b128 v[126:129], v42 offset:8192
	ds_read_b128 v[134:137], v43 offset:8192
	ds_read_b128 v[142:145], v44 offset:8192
	ds_read_b128 v[150:153], v45 offset:8192
	ds_read_b128 v[214:217], v46 offset:8192
	s_waitcnt lgkmcnt(14)
	v_mfma_f32_32x32x16_bf16 v[36:51], v[36:39], v[68:71], 0
	v_cndmask_b32_e32 v102, v103, v102, vcc
	v_mul_f32_e32 v103, 0xbfb8aa3b, v102
	v_fmamk_f32 v4, v4, 0x3fb8aa3b, v103
	v_fmamk_f32 v5, v5, 0x3fb8aa3b, v103
	v_exp_f32_e32 v4, v4
	v_fmamk_f32 v6, v6, 0x3fb8aa3b, v103
	v_exp_f32_e32 v5, v5
	v_mfma_f32_32x32x16_bf16 v[36:51], v[106:109], v[72:75], v[36:51]
	v_fmamk_f32 v7, v7, 0x3fb8aa3b, v103
	v_exp_f32_e32 v6, v6
	v_fmamk_f32 v8, v8, 0x3fb8aa3b, v103
	v_fmamk_f32 v9, v9, 0x3fb8aa3b, v103
	v_fmamk_f32 v10, v10, 0x3fb8aa3b, v103
	v_fmamk_f32 v11, v11, 0x3fb8aa3b, v103
	v_fmamk_f32 v12, v12, 0x3fb8aa3b, v103
	s_waitcnt lgkmcnt(13)
	v_mfma_f32_32x32x16_bf16 v[36:51], v[114:117], v[76:79], v[36:51]
	v_fmamk_f32 v13, v13, 0x3fb8aa3b, v103
	v_fmamk_f32 v14, v14, 0x3fb8aa3b, v103
	v_fmamk_f32 v15, v15, 0x3fb8aa3b, v103
	v_fmamk_f32 v16, v16, 0x3fb8aa3b, v103
	v_fmamk_f32 v17, v17, 0x3fb8aa3b, v103
	v_fmamk_f32 v18, v18, 0x3fb8aa3b, v103
	v_fmamk_f32 v19, v19, 0x3fb8aa3b, v103
	v_fmamk_f32 v20, v20, 0x3fb8aa3b, v103
	s_waitcnt lgkmcnt(12)
	v_mfma_f32_32x32x16_bf16 v[36:51], v[122:125], v[80:83], v[36:51]
	v_fmamk_f32 v21, v21, 0x3fb8aa3b, v103
	v_fmamk_f32 v22, v22, 0x3fb8aa3b, v103
	v_fmamk_f32 v23, v23, 0x3fb8aa3b, v103
	v_fmamk_f32 v24, v24, 0x3fb8aa3b, v103
	v_fmamk_f32 v25, v25, 0x3fb8aa3b, v103
	v_fmamk_f32 v26, v26, 0x3fb8aa3b, v103
	v_fmamk_f32 v27, v27, 0x3fb8aa3b, v103
	v_fmamk_f32 v28, v28, 0x3fb8aa3b, v103
	s_waitcnt lgkmcnt(11)
	v_mfma_f32_32x32x16_bf16 v[36:51], v[130:133], v[84:87], v[36:51]
	v_fmamk_f32 v29, v29, 0x3fb8aa3b, v103
	v_fmamk_f32 v30, v30, 0x3fb8aa3b, v103
	v_fmamk_f32 v31, v31, 0x3fb8aa3b, v103
	v_fmamk_f32 v32, v32, 0x3fb8aa3b, v103
	v_fmamk_f32 v33, v33, 0x3fb8aa3b, v103
	v_fmamk_f32 v34, v34, 0x3fb8aa3b, v103
	v_fmac_f32_e32 v103, 0x3fb8aa3b, v35
	v_exp_f32_e32 v7, v7
	s_waitcnt lgkmcnt(10)
	v_mfma_f32_32x32x16_bf16 v[36:51], v[138:141], v[88:91], v[36:51]
	v_exp_f32_e32 v8, v8
	v_exp_f32_e32 v35, v103
	v_add_f32_e32 v103, 0, v4
	v_exp_f32_e32 v9, v9
	s_waitcnt lgkmcnt(9)
	v_mfma_f32_32x32x16_bf16 v[36:51], v[146:149], v[92:95], v[36:51]
	v_add_f32_e32 v103, v5, v103
	v_exp_f32_e32 v10, v10
	v_add_f32_e32 v103, v6, v103
	v_exp_f32_e32 v11, v11
	v_add_f32_e32 v103, v7, v103
	v_exp_f32_e32 v12, v12
	s_waitcnt lgkmcnt(8)
	v_mfma_f32_32x32x16_bf16 v[36:51], v[154:157], v[96:99], v[36:51]
	v_add_f32_e32 v103, v8, v103
	v_exp_f32_e32 v13, v13
	v_add_f32_e32 v103, v9, v103
	v_exp_f32_e32 v14, v14
	v_add_f32_e32 v103, v10, v103
	s_waitcnt lgkmcnt(7)
	v_mfma_f32_32x32x16_bf16 v[52:67], v[52:55], v[68:71], 0
	v_exp_f32_e32 v15, v15
	v_add_f32_e32 v103, v11, v103
	v_exp_f32_e32 v16, v16
	v_add_f32_e32 v103, v12, v103
	v_exp_f32_e32 v17, v17
	s_waitcnt lgkmcnt(6)
	v_mfma_f32_32x32x16_bf16 v[52:67], v[110:113], v[72:75], v[52:67]
	v_add_f32_e32 v103, v13, v103
	v_exp_f32_e32 v18, v18
	v_add_f32_e32 v103, v14, v103
	v_exp_f32_e32 v19, v19
	v_add_f32_e32 v103, v15, v103
	v_exp_f32_e32 v20, v20
	s_waitcnt lgkmcnt(5)
	v_mfma_f32_32x32x16_bf16 v[52:67], v[118:121], v[76:79], v[52:67]
	v_add_f32_e32 v103, v16, v103
	v_exp_f32_e32 v21, v21
	v_add_f32_e32 v103, v17, v103
	v_exp_f32_e32 v22, v22
	v_add_f32_e32 v103, v18, v103
	s_waitcnt lgkmcnt(4)
	v_mfma_f32_32x32x16_bf16 v[52:67], v[126:129], v[80:83], v[52:67]
	v_exp_f32_e32 v23, v23
	v_add_f32_e32 v103, v19, v103
	v_exp_f32_e32 v24, v24
	v_add_f32_e32 v103, v20, v103
	v_exp_f32_e32 v25, v25
	s_waitcnt lgkmcnt(3)
	v_mfma_f32_32x32x16_bf16 v[52:67], v[134:137], v[84:87], v[52:67]
	v_add_f32_e32 v103, v21, v103
	v_exp_f32_e32 v26, v26
	v_add_f32_e32 v103, v22, v103
	v_exp_f32_e32 v27, v27
	v_add_f32_e32 v103, v23, v103
	v_exp_f32_e32 v28, v28
	s_waitcnt lgkmcnt(2)
	v_mfma_f32_32x32x16_bf16 v[52:67], v[142:145], v[88:91], v[52:67]
	v_add_f32_e32 v103, v24, v103
	v_exp_f32_e32 v29, v29
	v_add_f32_e32 v103, v25, v103
	v_exp_f32_e32 v30, v30
	v_add_f32_e32 v103, v26, v103
	s_waitcnt lgkmcnt(1)
	v_mfma_f32_32x32x16_bf16 v[52:67], v[150:153], v[92:95], v[52:67]
	v_exp_f32_e32 v31, v31
	v_add_f32_e32 v103, v27, v103
	v_exp_f32_e32 v32, v32
	v_add_f32_e32 v103, v28, v103
	v_exp_f32_e32 v33, v33
	s_waitcnt lgkmcnt(0)
	v_mfma_f32_32x32x16_bf16 v[52:67], v[214:217], v[96:99], v[52:67]
	v_add_f32_e32 v103, v29, v103
	v_exp_f32_e32 v34, v34
	v_add_f32_e32 v103, v30, v103
	v_add_f32_e32 v103, v31, v103
	v_add_f32_e32 v103, v32, v103
	v_add_f32_e32 v103, v33, v103
	v_add_f32_e32 v103, v34, v103
	s_branch .Lds_join_s2

.LBB0_1405:
	s_mul_hi_u32 s0, s57, 0xaaaaaaab
	s_lshr_b32 s0, s0, 1
	s_mul_i32 s0, s0, 0xc000
	s_sub_i32 s98, s60, s0
	v_add_u32_e32 v251, s98, v184
	v_add_u32_e32 v15, v251, v201
	v_add_u32_e32 v14, v251, v199
	v_add_u32_e32 v13, v251, v197
	v_add_u32_e32 v12, v251, v195
	v_add_u32_e32 v11, v251, v193
	v_add_u32_e32 v10, v251, v191
	v_add_u32_e32 v9, v251, v189
	v_add_u32_e32 v8, v251, v186
	ds_read_b128 v[4:7], v15
	ds_read_b128 v[110:113], v14
	ds_read_b128 v[118:121], v13
	ds_read_b128 v[126:129], v12
	ds_read_b128 v[134:137], v11
	ds_read_b128 v[142:145], v10
	ds_read_b128 v[150:153], v9
	ds_read_b128 v[214:217], v8
	ds_read_b128 v[20:23], v15 offset:8192
	ds_read_b128 v[114:117], v14 offset:8192
	ds_read_b128 v[122:125], v13 offset:8192
	ds_read_b128 v[130:133], v12 offset:8192
	ds_read_b128 v[138:141], v11 offset:8192
	ds_read_b128 v[146:149], v10 offset:8192
	ds_read_b128 v[154:157], v9 offset:8192
	ds_read_b128 v[218:221], v8 offset:8192
	s_waitcnt lgkmcnt(14)
	v_mfma_f32_32x32x16_bf16 v[4:19], v[4:7], v[68:71], 0
	v_cndmask_b32_e32 v102, v108, v102, vcc
	v_mul_f32_e32 v104, 0xbfb8aa3b, v102
	v_fmamk_f32 v36, v36, 0x3fb8aa3b, v104
	v_fmamk_f32 v37, v37, 0x3fb8aa3b, v104
	v_exp_f32_e32 v36, v36
	v_fmamk_f32 v38, v38, 0x3fb8aa3b, v104
	v_exp_f32_e32 v37, v37
	v_mfma_f32_32x32x16_bf16 v[4:19], v[110:113], v[72:75], v[4:19]
	v_fmamk_f32 v39, v39, 0x3fb8aa3b, v104
	v_exp_f32_e32 v38, v38
	v_fmamk_f32 v40, v40, 0x3fb8aa3b, v104
	v_exp_f32_e32 v39, v39
	v_add_f32_e32 v105, v105, v106
	v_fmamk_f32 v41, v41, 0x3fb8aa3b, v104
	s_waitcnt lgkmcnt(13)
	v_mfma_f32_32x32x16_bf16 v[4:19], v[118:121], v[76:79], v[4:19]
	v_exp_f32_e32 v40, v40
	v_fmac_f32_e32 v105, v100, v101
	v_add_f32_e32 v100, 0, v36
	v_fmamk_f32 v42, v42, 0x3fb8aa3b, v104
	v_exp_f32_e32 v41, v41
	v_add_f32_e32 v100, v37, v100
	v_fmamk_f32 v43, v43, 0x3fb8aa3b, v104
	s_waitcnt lgkmcnt(12)
	v_mfma_f32_32x32x16_bf16 v[4:19], v[126:129], v[80:83], v[4:19]
	v_exp_f32_e32 v42, v42
	v_add_f32_e32 v100, v38, v100
	v_fmamk_f32 v44, v44, 0x3fb8aa3b, v104
	v_exp_f32_e32 v43, v43
	v_add_f32_e32 v100, v39, v100
	v_fmamk_f32 v45, v45, 0x3fb8aa3b, v104
	s_waitcnt lgkmcnt(11)
	v_mfma_f32_32x32x16_bf16 v[4:19], v[134:137], v[84:87], v[4:19]
	v_exp_f32_e32 v44, v44
	v_add_f32_e32 v100, v40, v100
	v_fmamk_f32 v46, v46, 0x3fb8aa3b, v104
	v_exp_f32_e32 v45, v45
	v_add_f32_e32 v100, v41, v100
	v_fmamk_f32 v47, v47, 0x3fb8aa3b, v104
	v_exp_f32_e32 v46, v46
	s_waitcnt lgkmcnt(10)
	v_mfma_f32_32x32x16_bf16 v[4:19], v[142:145], v[88:91], v[4:19]
	v_add_f32_e32 v100, v42, v100
	v_fmamk_f32 v48, v48, 0x3fb8aa3b, v104
	v_exp_f32_e32 v47, v47
	v_add_f32_e32 v100, v43, v100
	v_fmamk_f32 v49, v49, 0x3fb8aa3b, v104
	v_exp_f32_e32 v48, v48
	s_waitcnt lgkmcnt(9)
	v_mfma_f32_32x32x16_bf16 v[4:19], v[150:153], v[92:95], v[4:19]
	v_add_f32_e32 v100, v44, v100
	v_fmamk_f32 v50, v50, 0x3fb8aa3b, v104
	v_exp_f32_e32 v49, v49
	v_add_f32_e32 v100, v45, v100
	v_fmamk_f32 v51, v51, 0x3fb8aa3b, v104
	v_exp_f32_e32 v50, v50
	s_waitcnt lgkmcnt(8)
	v_mfma_f32_32x32x16_bf16 v[4:19], v[214:217], v[96:99], v[4:19]
	v_add_f32_e32 v100, v46, v100
	v_fmamk_f32 v52, v52, 0x3fb8aa3b, v104
	v_exp_f32_e32 v51, v51
	v_add_f32_e32 v100, v47, v100
	v_fmamk_f32 v53, v53, 0x3fb8aa3b, v104
	v_exp_f32_e32 v52, v52
	s_waitcnt lgkmcnt(7)
	v_mfma_f32_32x32x16_bf16 v[20:35], v[20:23], v[68:71], 0
	v_add_f32_e32 v100, v48, v100
	v_fmamk_f32 v54, v54, 0x3fb8aa3b, v104
	v_exp_f32_e32 v53, v53
	v_add_f32_e32 v100, v49, v100
	v_fmamk_f32 v55, v55, 0x3fb8aa3b, v104
	v_exp_f32_e32 v54, v54
	s_waitcnt lgkmcnt(6)
	v_mfma_f32_32x32x16_bf16 v[20:35], v[114:117], v[72:75], v[20:35]
	v_add_f32_e32 v100, v50, v100
	v_fmamk_f32 v56, v56, 0x3fb8aa3b, v104
	v_exp_f32_e32 v55, v55
	v_add_f32_e32 v100, v51, v100
	v_fmamk_f32 v57, v57, 0x3fb8aa3b, v104
	v_exp_f32_e32 v56, v56
	v_add_f32_e32 v100, v52, v100
	s_waitcnt lgkmcnt(5)
	v_mfma_f32_32x32x16_bf16 v[20:35], v[122:125], v[76:79], v[20:35]
	v_fmamk_f32 v58, v58, 0x3fb8aa3b, v104
	v_exp_f32_e32 v57, v57
	v_add_f32_e32 v100, v53, v100
	v_fmamk_f32 v59, v59, 0x3fb8aa3b, v104
	v_exp_f32_e32 v58, v58
	v_add_f32_e32 v100, v54, v100
	s_waitcnt lgkmcnt(4)
	v_mfma_f32_32x32x16_bf16 v[20:35], v[130:133], v[80:83], v[20:35]
	v_fmamk_f32 v60, v60, 0x3fb8aa3b, v104
	v_exp_f32_e32 v59, v59
	v_add_f32_e32 v100, v55, v100
	v_fmamk_f32 v61, v61, 0x3fb8aa3b, v104
	v_exp_f32_e32 v60, v60
	v_add_f32_e32 v100, v56, v100
	v_fmamk_f32 v62, v62, 0x3fb8aa3b, v104
	s_waitcnt lgkmcnt(3)
	v_mfma_f32_32x32x16_bf16 v[20:35], v[138:141], v[84:87], v[20:35]
	v_exp_f32_e32 v61, v61
	v_add_f32_e32 v100, v57, v100
	v_fmamk_f32 v63, v63, 0x3fb8aa3b, v104
	v_exp_f32_e32 v62, v62
	v_add_f32_e32 v100, v58, v100
	v_fmamk_f32 v64, v64, 0x3fb8aa3b, v104
	s_waitcnt lgkmcnt(2)
	v_mfma_f32_32x32x16_bf16 v[20:35], v[146:149], v[88:91], v[20:35]
	v_exp_f32_e32 v63, v63
	v_add_f32_e32 v100, v59, v100
	v_fmamk_f32 v65, v65, 0x3fb8aa3b, v104
	v_exp_f32_e32 v64, v64
	v_add_f32_e32 v100, v60, v100
	v_fmamk_f32 v66, v66, 0x3fb8aa3b, v104
	v_exp_f32_e32 v65, v65
	s_waitcnt lgkmcnt(1)
	v_mfma_f32_32x32x16_bf16 v[20:35], v[154:157], v[92:95], v[20:35]
	v_add_f32_e32 v100, v61, v100
	v_fmac_f32_e32 v104, 0x3fb8aa3b, v67
	v_exp_f32_e32 v66, v66
	v_add_f32_e32 v100, v62, v100
	v_exp_f32_e32 v67, v104
	s_waitcnt lgkmcnt(0)
	v_mfma_f32_32x32x16_bf16 v[20:35], v[218:221], v[96:99], v[20:35]
	v_add_f32_e32 v100, v63, v100
	v_add_f32_e32 v100, v64, v100
	v_add_f32_e32 v100, v65, v100
	v_add_f32_e32 v100, v66, v100
	v_add_f32_e32 v100, v67, v100
	v_mov_b32_e32 v101, v100
	s_nop 1
	v_permlane32_swap_b32_e32 v100, v101
	s_branch .Lds_join_s3
